# v20a with the FFN_DOWN k-loop rewritten around LDS-DMA (global_load_lds_dwordx4 straight into the swizzled LDS image, source-side swizzle, loads issued at the head of each iteration, one barrier per i
# baseline (speedup 1.0000x reference)
.LBB0_107:
	s_load_dwordx4 s[40:43], s[0:1], 0xe8
	v_mov_b32_e32 v201, v206
	s_lshl_b32 s62, s44, 8
	s_load_dwordx2 s[64:65], s[20:21], 0x0
	s_mul_i32 s49, s45, 0x1600
	s_mul_hi_i32 s48, s45, 0x1600
	v_ashrrev_i32_e32 v40, 3, v201
	s_waitcnt lgkmcnt(0)
	s_add_u32 s20, s42, s49
	v_lshlrev_b32_e32 v0, 4, v201
	v_mul_lo_u32 v2, v40, s93
	s_movk_i32 s5, 0x70
	s_addc_u32 s21, s43, s48
	s_ashr_i32 s63, s62, 31
	s_mul_i32 s61, s44, 0x160000
	v_and_or_b32 v0, v0, s5, v2
	s_mul_hi_i32 s72, s62, 0x1600
	s_add_u32 s40, s50, s61
	v_add_u32_e32 v34, 0x58000, v0
	v_add_u32_e32 v36, 0xb0000, v0
	s_addc_u32 s41, s51, s72
	global_load_dwordx4 v[2:5], v0, s[20:21]
	global_load_dwordx4 v[6:9], v0, s[40:41]
	global_load_dwordx4 v[10:13], v34, s[20:21]
	global_load_dwordx4 v[14:17], v34, s[40:41]
	global_load_dwordx4 v[18:21], v36, s[20:21]
	global_load_dwordx4 v[22:25], v36, s[40:41]
	v_add_u32_e32 v38, 0x108000, v0
	global_load_dwordx4 v[26:29], v38, s[20:21]
	global_load_dwordx4 v[30:33], v38, s[40:41]
	global_load_dwordx4 v[144:147], v0, s[20:21] offset:128
	global_load_dwordx4 v[148:151], v0, s[40:41] offset:128
	global_load_dwordx4 v[152:155], v34, s[20:21] offset:128
	global_load_dwordx4 v[156:159], v34, s[40:41] offset:128
	global_load_dwordx4 v[160:163], v36, s[20:21] offset:128
	global_load_dwordx4 v[164:167], v36, s[40:41] offset:128
	global_load_dwordx4 v[168:171], v38, s[20:21] offset:128
	global_load_dwordx4 v[172:175], v38, s[40:41] offset:128
	v_lshlrev_b32_e32 v48, 7, v40
	v_lshrrev_b32_e32 v40, 1, v40
	s_movk_i32 s4, 0x100
	v_xor_b32_e32 v40, v40, v201
	s_add_u32 s20, s89, s61
	v_mov_b32_e32 v35, v1
	v_mov_b32_e32 v37, v1
	v_mov_b32_e32 v39, v1
	v_cmp_gt_u32_e64 s[44:45], s4, v201
	v_lshlrev_b32_e32 v40, 4, v40
	s_addc_u32 s21, s90, s72
	v_readlane_b32 s4, v254, 35
	v_lshlrev_b32_e32 v42, 7, v201
	v_bfe_u32 v43, v201, 1, 3
	v_lshrrev_b32_e32 v229, 5, v201
	v_bfe_u32 v204, v201, 5, 1
	v_and_or_b32 v198, v40, s5, v48
	v_lshl_add_u64 v[176:177], s[20:21], 0, v[38:39]
	v_lshl_add_u64 v[178:179], s[20:21], 0, v[36:37]
	v_lshl_add_u64 v[180:181], s[20:21], 0, v[34:35]
	v_lshl_add_u64 v[182:183], s[20:21], 0, v[0:1]
	s_add_u32 s20, s4, s49
	v_readlane_b32 s4, v254, 36
	v_ashrrev_i32_e32 v41, 8, v201
	v_and_b32_e32 v44, 0xf80, v42
	v_and_b32_e32 v42, 0x6f80, v42
	v_bitop3_b32 v45, v229, v43, 1 bitop3:0x6c
	v_bitop3_b32 v46, v204, v43, 2 bitop3:0x36
	v_bitop3_b32 v47, v204, v43, 4 bitop3:0x36
	v_bitop3_b32 v43, v204, v43, 6 bitop3:0x36
	s_addc_u32 s21, s4, s48
	v_cmp_eq_u32_e64 s[42:43], 1, v41
	v_cmp_ne_u32_e64 s[46:47], 1, v41
	v_lshl_or_b32 v192, v41, 14, v44
	v_or_b32_e32 v193, 0x8000, v42
	v_lshlrev_b32_e32 v194, 4, v45
	v_lshlrev_b32_e32 v195, 4, v46
	v_lshlrev_b32_e32 v196, 4, v47
	v_lshlrev_b32_e32 v197, 4, v43
	v_lshl_add_u64 v[184:185], s[20:21], 0, v[38:39]
	v_lshl_add_u64 v[186:187], s[20:21], 0, v[36:37]
	v_lshl_add_u64 v[188:189], s[20:21], 0, v[34:35]
	v_lshl_add_u64 v[190:191], s[20:21], 0, v[0:1]
	v_mov_b32_e32 v0, v1
	v_cmp_lt_u32_e32 vcc, s76, v201
	s_mov_b64 s[20:21], 0
	s_mov_b32 s61, 0
	s_mov_b32 s72, 0
	s_waitcnt vmcnt(15)
	ds_write_b128 v198, v[2:5]
	s_waitcnt vmcnt(14)
	ds_write_b128 v198, v[6:9] offset:32768
	s_waitcnt vmcnt(13)
	ds_write_b128 v198, v[10:13] offset:8192
	s_waitcnt vmcnt(12)
	ds_write_b128 v198, v[14:17] offset:40960
	s_waitcnt vmcnt(11)
	ds_write_b128 v198, v[18:21] offset:16384
	s_waitcnt vmcnt(10)
	ds_write_b128 v198, v[22:25] offset:49152
	s_waitcnt vmcnt(9)
	ds_write_b128 v198, v[26:29] offset:24576
	s_waitcnt vmcnt(8)
	ds_write_b128 v198, v[30:33] offset:57344
	v_mov_b32_e32 v14, v1
	v_mov_b32_e32 v15, v1
	v_mov_b32_e32 v2, v1
	v_mov_b32_e32 v3, v1
	v_mov_b32_e32 v4, v1
	v_mov_b32_e32 v5, v1
	v_mov_b32_e32 v6, v1
	v_mov_b32_e32 v7, v1
	v_mov_b32_e32 v8, v1
	v_mov_b32_e32 v9, v1
	v_mov_b32_e32 v10, v1
	v_mov_b32_e32 v11, v1
	v_mov_b32_e32 v12, v1
	v_mov_b32_e32 v13, v1
	v_mov_b64_e32 v[30:31], v[14:15]
	v_mov_b64_e32 v[46:47], v[14:15]
	v_mov_b64_e32 v[62:63], v[14:15]
	v_mov_b64_e32 v[78:79], v[14:15]
	v_mov_b64_e32 v[94:95], v[14:15]
	v_mov_b64_e32 v[110:111], v[14:15]
	v_mov_b64_e32 v[126:127], v[14:15]
	v_mov_b64_e32 v[142:143], v[14:15]
	v_mov_b64_e32 v[28:29], v[12:13]
	v_mov_b64_e32 v[26:27], v[10:11]
	v_mov_b64_e32 v[24:25], v[8:9]
	v_mov_b64_e32 v[22:23], v[6:7]
	v_mov_b64_e32 v[20:21], v[4:5]
	v_mov_b64_e32 v[18:19], v[2:3]
	v_mov_b64_e32 v[16:17], v[0:1]
	v_mov_b64_e32 v[44:45], v[12:13]
	v_mov_b64_e32 v[42:43], v[10:11]
	v_mov_b64_e32 v[40:41], v[8:9]
	v_mov_b64_e32 v[38:39], v[6:7]
	v_mov_b64_e32 v[36:37], v[4:5]
	v_mov_b64_e32 v[34:35], v[2:3]
	v_mov_b64_e32 v[32:33], v[0:1]
	v_mov_b64_e32 v[60:61], v[12:13]
	v_mov_b64_e32 v[58:59], v[10:11]
	v_mov_b64_e32 v[56:57], v[8:9]
	v_mov_b64_e32 v[54:55], v[6:7]
	v_mov_b64_e32 v[52:53], v[4:5]
	v_mov_b64_e32 v[50:51], v[2:3]
	v_mov_b64_e32 v[48:49], v[0:1]
	v_mov_b64_e32 v[76:77], v[12:13]
	v_mov_b64_e32 v[74:75], v[10:11]
	v_mov_b64_e32 v[72:73], v[8:9]
	v_mov_b64_e32 v[70:71], v[6:7]
	v_mov_b64_e32 v[68:69], v[4:5]
	v_mov_b64_e32 v[66:67], v[2:3]
	v_mov_b64_e32 v[64:65], v[0:1]
	v_mov_b64_e32 v[92:93], v[12:13]
	v_mov_b64_e32 v[90:91], v[10:11]
	v_mov_b64_e32 v[88:89], v[8:9]
	v_mov_b64_e32 v[86:87], v[6:7]
	v_mov_b64_e32 v[84:85], v[4:5]
	v_mov_b64_e32 v[82:83], v[2:3]
	v_mov_b64_e32 v[80:81], v[0:1]
	v_mov_b64_e32 v[108:109], v[12:13]
	v_mov_b64_e32 v[106:107], v[10:11]
	v_mov_b64_e32 v[104:105], v[8:9]
	v_mov_b64_e32 v[102:103], v[6:7]
	v_mov_b64_e32 v[100:101], v[4:5]
	v_mov_b64_e32 v[98:99], v[2:3]
	v_mov_b64_e32 v[96:97], v[0:1]
	v_mov_b64_e32 v[124:125], v[12:13]
	v_mov_b64_e32 v[122:123], v[10:11]
	v_mov_b64_e32 v[120:121], v[8:9]
	v_mov_b64_e32 v[118:119], v[6:7]
	v_mov_b64_e32 v[116:117], v[4:5]
	v_mov_b64_e32 v[114:115], v[2:3]
	v_mov_b64_e32 v[112:113], v[0:1]
	v_mov_b64_e32 v[140:141], v[12:13]
	v_mov_b64_e32 v[138:139], v[10:11]
	v_mov_b64_e32 v[136:137], v[8:9]
	v_mov_b64_e32 v[134:135], v[6:7]
	v_mov_b64_e32 v[132:133], v[4:5]
	v_mov_b64_e32 v[130:131], v[2:3]
	v_mov_b64_e32 v[128:129], v[0:1]
	v_lshrrev_b32_e32 v212, 6, v206
	v_bfe_u32 v213, v206, 4, 3
	v_readfirstlane_b32 s41, v212
	v_and_b32_e32 v212, 7, v206
	s_lshl_b32 s41, s41, 10
	v_xor_b32_e32 v213, v213, v212
	v_sub_u32_e32 v212, v213, v212
	v_lshlrev_b32_e32 v212, 4, v212
	v_add_u32_e32 v212, 0xffffff80, v212
	v_ashrrev_i32_e32 v213, 31, v212
	v_lshl_add_u64 v[190:191], v[190:191], 0, v[212:213]
	v_lshl_add_u64 v[182:183], v[182:183], 0, v[212:213]
	v_lshl_add_u64 v[188:189], v[188:189], 0, v[212:213]
	v_lshl_add_u64 v[180:181], v[180:181], 0, v[212:213]
	v_lshl_add_u64 v[186:187], v[186:187], 0, v[212:213]
	v_lshl_add_u64 v[178:179], v[178:179], 0, v[212:213]
	v_lshl_add_u64 v[184:185], v[184:185], 0, v[212:213]
	v_lshl_add_u64 v[176:177], v[176:177], 0, v[212:213]
	s_mov_b64 exec, -1
	s_waitcnt lgkmcnt(0)
	s_barrier
	s_branch .LBB0_109
.LBB0_108:
	s_add_u32 s20, s20, 0x80
	s_addc_u32 s21, s21, 0
	s_add_i32 s72, s72, 0x10000
	s_add_i32 s61, s61, 1
	s_cmpk_eq_i32 s20, 0x1600
	s_waitcnt vmcnt(0) lgkmcnt(0)
	s_barrier
	s_cbranch_scc1 .LBB0_123
.LBB0_109:
	s_and_b32 s40, s72, 0x10000
	v_add_u32_e32 v0, s40, v192
	v_or_b32_e32 v2, s40, v193
	v_add_u32_e32 v14, v0, v194
	v_add_u32_e32 v15, v0, v195
	v_add_u32_e32 v199, v0, v196
	v_add_u32_e32 v0, v0, v197
	v_add_u32_e32 v205, v2, v194
	v_add_u32_e32 v228, v2, v195
	v_add_u32_e32 v250, v2, v196
	v_add_u32_e32 v251, v2, v197
	s_cmp_gt_u32 s61, 42
	s_cbranch_scc1 .Ldma_nl
	s_andn2_b32 s40, 0x10000, s72
	s_add_i32 s40, s40, s41
	s_mov_b32 m0, s40
	v_lshl_add_u64 v[212:213], v[190:191], 0, s[20:21]
	global_load_lds_dwordx4 v[212:213], off
	s_add_i32 m0, s40, 0x8000
	v_lshl_add_u64 v[212:213], v[182:183], 0, s[20:21]
	global_load_lds_dwordx4 v[212:213], off
	s_add_i32 m0, s40, 0x2000
	v_lshl_add_u64 v[212:213], v[188:189], 0, s[20:21]
	global_load_lds_dwordx4 v[212:213], off
	s_add_i32 m0, s40, 0xa000
	v_lshl_add_u64 v[212:213], v[180:181], 0, s[20:21]
	global_load_lds_dwordx4 v[212:213], off
	s_add_i32 m0, s40, 0x4000
	v_lshl_add_u64 v[212:213], v[186:187], 0, s[20:21]
	global_load_lds_dwordx4 v[212:213], off
	s_add_i32 m0, s40, 0xc000
	v_lshl_add_u64 v[212:213], v[178:179], 0, s[20:21]
	global_load_lds_dwordx4 v[212:213], off
	s_add_i32 m0, s40, 0x6000
	v_lshl_add_u64 v[212:213], v[184:185], 0, s[20:21]
	global_load_lds_dwordx4 v[212:213], off
	s_add_i32 m0, s40, 0xe000
	v_lshl_add_u64 v[212:213], v[176:177], 0, s[20:21]
	global_load_lds_dwordx4 v[212:213], off
	s_setprio 1
	ds_read_b128 v[2:5], v14 offset:0
	ds_read_b128 v[6:9], v14 offset:4096
	ds_read_b128 v[10:13], v14 offset:8192
	ds_read_b128 v[208:211], v14 offset:12288
	ds_read_b128 v[242:245], v205 offset:0
	ds_read_b128 v[246:249], v205 offset:4096
	ds_read_b128 v[214:217], v15 offset:0
	ds_read_b128 v[230:233], v15 offset:4096
	ds_read_b128 v[234:237], v15 offset:8192
	ds_read_b128 v[238:241], v15 offset:12288
	s_waitcnt lgkmcnt(4)
	v_mfma_f32_32x32x16_bf16 v[128:143], v[2:5], v[242:245], v[128:143]
	v_mfma_f32_32x32x16_bf16 v[96:111], v[6:9], v[242:245], v[96:111]
	v_mfma_f32_32x32x16_bf16 v[64:79], v[10:13], v[242:245], v[64:79]
	v_mfma_f32_32x32x16_bf16 v[32:47], v[208:211], v[242:245], v[32:47]
	ds_read_b128 v[242:245], v228 offset:0
	v_mfma_f32_32x32x16_bf16 v[112:127], v[2:5], v[246:249], v[112:127]
	v_mfma_f32_32x32x16_bf16 v[80:95], v[6:9], v[246:249], v[80:95]
	v_mfma_f32_32x32x16_bf16 v[48:63], v[10:13], v[246:249], v[48:63]
	v_mfma_f32_32x32x16_bf16 v[16:31], v[208:211], v[246:249], v[16:31]
	ds_read_b128 v[246:249], v228 offset:4096
	ds_read_b128 v[2:5], v199 offset:0
	ds_read_b128 v[6:9], v199 offset:4096
	ds_read_b128 v[10:13], v199 offset:8192
	ds_read_b128 v[208:211], v199 offset:12288
	s_waitcnt lgkmcnt(5)
	v_mfma_f32_32x32x16_bf16 v[128:143], v[214:217], v[242:245], v[128:143]
	v_mfma_f32_32x32x16_bf16 v[96:111], v[230:233], v[242:245], v[96:111]
	v_mfma_f32_32x32x16_bf16 v[64:79], v[234:237], v[242:245], v[64:79]
	v_mfma_f32_32x32x16_bf16 v[32:47], v[238:241], v[242:245], v[32:47]
	ds_read_b128 v[242:245], v250 offset:0
	s_waitcnt lgkmcnt(5)
	v_mfma_f32_32x32x16_bf16 v[112:127], v[214:217], v[246:249], v[112:127]
	v_mfma_f32_32x32x16_bf16 v[80:95], v[230:233], v[246:249], v[80:95]
	v_mfma_f32_32x32x16_bf16 v[48:63], v[234:237], v[246:249], v[48:63]
	v_mfma_f32_32x32x16_bf16 v[16:31], v[238:241], v[246:249], v[16:31]
	ds_read_b128 v[246:249], v250 offset:4096
	ds_read_b128 v[214:217], v0 offset:0
	ds_read_b128 v[230:233], v0 offset:4096
	ds_read_b128 v[234:237], v0 offset:8192
	ds_read_b128 v[238:241], v0 offset:12288
	s_waitcnt lgkmcnt(5)
	v_mfma_f32_32x32x16_bf16 v[128:143], v[2:5], v[242:245], v[128:143]
	v_mfma_f32_32x32x16_bf16 v[96:111], v[6:9], v[242:245], v[96:111]
	v_mfma_f32_32x32x16_bf16 v[64:79], v[10:13], v[242:245], v[64:79]
	v_mfma_f32_32x32x16_bf16 v[32:47], v[208:211], v[242:245], v[32:47]
	ds_read_b128 v[242:245], v251 offset:0
	s_waitcnt lgkmcnt(5)
	v_mfma_f32_32x32x16_bf16 v[112:127], v[2:5], v[246:249], v[112:127]
	v_mfma_f32_32x32x16_bf16 v[80:95], v[6:9], v[246:249], v[80:95]
	v_mfma_f32_32x32x16_bf16 v[48:63], v[10:13], v[246:249], v[48:63]
	v_mfma_f32_32x32x16_bf16 v[16:31], v[208:211], v[246:249], v[16:31]
	ds_read_b128 v[246:249], v251 offset:4096
	s_waitcnt lgkmcnt(1)
	v_mfma_f32_32x32x16_bf16 v[128:143], v[214:217], v[242:245], v[128:143]
	v_mfma_f32_32x32x16_bf16 v[96:111], v[230:233], v[242:245], v[96:111]
	v_mfma_f32_32x32x16_bf16 v[64:79], v[234:237], v[242:245], v[64:79]
	v_mfma_f32_32x32x16_bf16 v[32:47], v[238:241], v[242:245], v[32:47]
	s_waitcnt lgkmcnt(0)
	v_mfma_f32_32x32x16_bf16 v[112:127], v[214:217], v[246:249], v[112:127]
	v_mfma_f32_32x32x16_bf16 v[80:95], v[230:233], v[246:249], v[80:95]
	v_mfma_f32_32x32x16_bf16 v[48:63], v[234:237], v[246:249], v[48:63]
	v_mfma_f32_32x32x16_bf16 v[16:31], v[238:241], v[246:249], v[16:31]
	s_nop 15
	s_nop 7

	s_setprio 0
	s_branch .LBB0_108
.Ldma_nl:
	s_setprio 1
	ds_read_b128 v[2:5], v14 offset:0
	ds_read_b128 v[6:9], v14 offset:4096
	ds_read_b128 v[10:13], v14 offset:8192
	ds_read_b128 v[208:211], v14 offset:12288
	ds_read_b128 v[242:245], v205 offset:0
	ds_read_b128 v[246:249], v205 offset:4096
	ds_read_b128 v[214:217], v15 offset:0
	ds_read_b128 v[230:233], v15 offset:4096
	ds_read_b128 v[234:237], v15 offset:8192
	ds_read_b128 v[238:241], v15 offset:12288
	s_waitcnt lgkmcnt(4)
	v_mfma_f32_32x32x16_bf16 v[128:143], v[2:5], v[242:245], v[128:143]
	v_mfma_f32_32x32x16_bf16 v[96:111], v[6:9], v[242:245], v[96:111]
	v_mfma_f32_32x32x16_bf16 v[64:79], v[10:13], v[242:245], v[64:79]
	v_mfma_f32_32x32x16_bf16 v[32:47], v[208:211], v[242:245], v[32:47]
	ds_read_b128 v[242:245], v228 offset:0
	v_mfma_f32_32x32x16_bf16 v[112:127], v[2:5], v[246:249], v[112:127]
	v_mfma_f32_32x32x16_bf16 v[80:95], v[6:9], v[246:249], v[80:95]
	v_mfma_f32_32x32x16_bf16 v[48:63], v[10:13], v[246:249], v[48:63]
	v_mfma_f32_32x32x16_bf16 v[16:31], v[208:211], v[246:249], v[16:31]
	ds_read_b128 v[246:249], v228 offset:4096
	ds_read_b128 v[2:5], v199 offset:0
	ds_read_b128 v[6:9], v199 offset:4096
	ds_read_b128 v[10:13], v199 offset:8192
	ds_read_b128 v[208:211], v199 offset:12288
	s_waitcnt lgkmcnt(5)
	v_mfma_f32_32x32x16_bf16 v[128:143], v[214:217], v[242:245], v[128:143]
	v_mfma_f32_32x32x16_bf16 v[96:111], v[230:233], v[242:245], v[96:111]
	v_mfma_f32_32x32x16_bf16 v[64:79], v[234:237], v[242:245], v[64:79]
	v_mfma_f32_32x32x16_bf16 v[32:47], v[238:241], v[242:245], v[32:47]
	ds_read_b128 v[242:245], v250 offset:0
	s_waitcnt lgkmcnt(5)
	v_mfma_f32_32x32x16_bf16 v[112:127], v[214:217], v[246:249], v[112:127]
	v_mfma_f32_32x32x16_bf16 v[80:95], v[230:233], v[246:249], v[80:95]
	v_mfma_f32_32x32x16_bf16 v[48:63], v[234:237], v[246:249], v[48:63]
	v_mfma_f32_32x32x16_bf16 v[16:31], v[238:241], v[246:249], v[16:31]
	ds_read_b128 v[246:249], v250 offset:4096
	ds_read_b128 v[214:217], v0 offset:0
	ds_read_b128 v[230:233], v0 offset:4096
	ds_read_b128 v[234:237], v0 offset:8192
	ds_read_b128 v[238:241], v0 offset:12288
	s_waitcnt lgkmcnt(5)
	v_mfma_f32_32x32x16_bf16 v[128:143], v[2:5], v[242:245], v[128:143]
	v_mfma_f32_32x32x16_bf16 v[96:111], v[6:9], v[242:245], v[96:111]
	v_mfma_f32_32x32x16_bf16 v[64:79], v[10:13], v[242:245], v[64:79]
	v_mfma_f32_32x32x16_bf16 v[32:47], v[208:211], v[242:245], v[32:47]
	ds_read_b128 v[242:245], v251 offset:0
	s_waitcnt lgkmcnt(5)
	v_mfma_f32_32x32x16_bf16 v[112:127], v[2:5], v[246:249], v[112:127]
	v_mfma_f32_32x32x16_bf16 v[80:95], v[6:9], v[246:249], v[80:95]
	v_mfma_f32_32x32x16_bf16 v[48:63], v[10:13], v[246:249], v[48:63]
	v_mfma_f32_32x32x16_bf16 v[16:31], v[208:211], v[246:249], v[16:31]
	ds_read_b128 v[246:249], v251 offset:4096
	s_waitcnt lgkmcnt(1)
	v_mfma_f32_32x32x16_bf16 v[128:143], v[214:217], v[242:245], v[128:143]
	v_mfma_f32_32x32x16_bf16 v[96:111], v[230:233], v[242:245], v[96:111]
	v_mfma_f32_32x32x16_bf16 v[64:79], v[234:237], v[242:245], v[64:79]
	v_mfma_f32_32x32x16_bf16 v[32:47], v[238:241], v[242:245], v[32:47]
	s_waitcnt lgkmcnt(0)
	v_mfma_f32_32x32x16_bf16 v[112:127], v[214:217], v[246:249], v[112:127]
	v_mfma_f32_32x32x16_bf16 v[80:95], v[230:233], v[246:249], v[80:95]
	v_mfma_f32_32x32x16_bf16 v[48:63], v[234:237], v[246:249], v[48:63]
	v_mfma_f32_32x32x16_bf16 v[16:31], v[238:241], v[246:249], v[16:31]
	s_nop 15
	s_nop 7

	s_setprio 0
	s_branch .LBB0_108
